# attention: fixed softmax reference R from tracked norms, removed running-max tree/rescale and pad nops (no fallback guard yet)
# speedup vs baseline: 1.0084x; 1.0084x over previous
.LBB0_306:
	s_or_b64 exec, exec, s[0:1]
	v_readlane_b32 s0, v252, 1
	v_mov_b32_e32 v169, 0
	v_readlane_b32 s1, v252, 2
	v_mov_b32_e32 v5, 0x8000
	s_waitcnt lgkmcnt(0)
	s_barrier
	v_add_f32_e32 v2, v0, v2
	s_nop 0
	global_load_dword v4, v169, s[0:1] sc1
	v_add_f32_e32 v1, v1, v3
	global_load_dword v5, v5, s[62:63] offset:768 sc1
	s_mov_b32 s0, 0x3fb8aa3b
	v_lshrrev_b32_e32 v7, 4, v209
	v_lshlrev_b32_e32 v10, 4, v209
	v_mul_f32_e32 v13, 0x3fb8aa3b, v2
	v_lshrrev_b32_e32 v8, 5, v209
	v_lshrrev_b32_e32 v9, 3, v209
	v_mul_f32_e32 v14, 0x3fb8aa3b, v1
	v_and_b32_e32 v15, 51, v7
	v_and_b32_e32 v17, 0xf0, v10
	v_mul_u32_u24_e32 v7, 0x1400, v7
	v_fma_f32 v20, v2, s0, -v13
	v_rndne_f32_e32 v21, v13
	v_and_b32_e32 v8, 4, v8
	v_and_b32_e32 v16, 8, v9
	v_fma_f32 v22, v1, s0, -v14
	v_rndne_f32_e32 v23, v14
	v_or_b32_e32 v170, v17, v7
	v_fmac_f32_e32 v20, 0x32a5705f, v2
	v_sub_f32_e32 v7, v13, v21
	v_or3_b32 v8, v15, v8, v16
	v_fmac_f32_e32 v22, 0x32a5705f, v1
	v_sub_f32_e32 v14, v14, v23
	v_add_f32_e32 v7, v7, v20
	v_cvt_i32_f32_e32 v13, v21
	v_mul_u32_u24_e32 v8, 0x110, v8
	v_add_f32_e32 v14, v14, v22
	v_exp_f32_e32 v7, v7
	v_cvt_i32_f32_e32 v15, v23
	v_add3_u32 v212, 0, v8, v17
	v_exp_f32_e32 v8, v14
	s_mov_b32 s1, 0xc2ce8ed0
	v_ldexp_f32 v7, v7, v13
	v_cmp_ngt_f32_e32 vcc, s1, v2
	s_mov_b32 s33, 0x42b17218
	v_ldexp_f32 v8, v8, v15
	v_cndmask_b32_e32 v7, 0, v7, vcc
	v_cmp_ngt_f32_e32 vcc, s1, v1
	v_mov_b32_e32 v3, 0x7f800000
	s_mov_b32 s38, 0xf800000
	v_cndmask_b32_e32 v8, 0, v8, vcc
	v_cmp_nlt_f32_e32 vcc, s33, v2
	s_add_u32 s4, s62, 0xc00000
	s_addc_u32 s5, s63, 0
	v_cndmask_b32_e32 v2, v3, v7, vcc
	v_cmp_nlt_f32_e32 vcc, s33, v1
	s_add_u32 s6, s62, 0xd00000
	s_addc_u32 s7, s63, 0
	v_cndmask_b32_e32 v1, v3, v8, vcc
	v_sub_f32_e32 v1, v2, v1
	v_add_f32_e32 v172, 0x3eb60549, v1
	s_add_u32 s34, s62, 0xe00000
	s_addc_u32 s35, s63, 0
	s_add_u32 s26, s62, 0x1000000
	s_addc_u32 s27, s63, 0
	v_mov_b32_e32 v6, 0x260
	s_add_u32 s24, s62, 0x1b00000
	s_addc_u32 s25, s63, 0
	s_add_u32 s36, s62, 0x1c900000
	s_addc_u32 s37, s63, 0
	v_mul_u32_u24_e32 v11, 0x110, v167
	v_lshlrev_b32_e32 v12, 4, v166
	s_add_u32 s40, s62, 0x8000
	s_addc_u32 s41, s63, 0
	v_add3_u32 v214, 0, v11, v12
	v_lshlrev_b32_e32 v0, 3, v166
	s_add_i32 s66, s64, 0xa00
	v_lshlrev_b32_e32 v168, 2, v167
	v_and_b32_e32 v18, 0x70, v10
	v_mul_u32_u24_e32 v19, 0x10080, v9
	v_mul_u32_u24_e32 v9, 0x90, v9
	v_lshl_add_u64 v[194:195], s[30:31], 0, v[168:169]
	s_movk_i32 s30, 0xff80
	s_mov_b32 s44, 0xfffb0000
	s_movk_i32 s13, 0x1400
	v_mov_b32_e32 v171, v169
	v_lshl_add_u32 v216, v129, 2, 0
	v_lshl_add_u64 v[174:175], s[56:57], 0, v[168:169]
	s_movk_i32 s67, 0x84
	v_or_b32_e32 v219, 8, v177
	s_waitcnt vmcnt(0)
	v_mul_f32_e32 v2, v4, v5
	v_mul_f32_e32 v3, 0x4f800000, v2
	v_cmp_gt_f32_e32 vcc, s38, v2
	v_or_b32_e32 v220, 16, v177
	v_or_b32_e32 v221, 24, v177
	v_cndmask_b32_e32 v2, v2, v3, vcc
	v_sqrt_f32_e32 v3, v2
	v_lshl_add_u64 v[180:181], s[54:55], 0, v[168:169]
	v_lshl_add_u64 v[184:185], s[52:53], 0, v[168:169]
	v_lshl_add_u64 v[186:187], s[48:49], 0, v[168:169]
	v_add_u32_e32 v1, -1, v3
	v_add_u32_e32 v4, 1, v3
	v_fma_f32 v5, -v1, v3, v2
	v_fma_f32 v7, -v4, v3, v2
	v_cmp_ge_f32_e64 s[0:1], 0, v5
	v_mov_b32_e32 v5, v169
	v_lshl_add_u64 v[190:191], s[46:47], 0, v[168:169]
	v_cndmask_b32_e64 v1, v3, v1, s[0:1]
	v_cmp_lt_f32_e64 s[0:1], 0, v7
	v_mov_b32_e32 v173, v172
	v_mov_b32_e32 v165, v166
	v_cndmask_b32_e64 v1, v1, v4, s[0:1]
	v_mul_f32_e32 v3, 0x37800000, v1
	v_cndmask_b32_e32 v1, v1, v3, vcc
	v_cmp_class_f32_e32 vcc, v2, v6
	s_add_i32 s0, 0, 0x12000
	v_add_u32_e32 v217, s0, v12
	v_cndmask_b32_e32 v1, v1, v2, vcc
	v_add_f32_e32 v1, v1, v1
	v_mul_f32_e32 v1, 0x3f828f5c, v1
	v_sub_f32_e32 v253, 0, v1
	v_fmaak_f32 v213, 2.0, v1, 0x43160000
	v_lshlrev_b32_e32 v1, 7, v167
	v_sub_u32_e32 v215, v214, v1
	s_mul_i32 s0, s78, 0x2200
	v_and_b32_e32 v1, 56, v200
	s_add_i32 s0, s0, 0
	v_mul_u32_u24_e32 v3, 0x84, v1
	v_lshlrev_b32_e32 v4, 1, v1
	v_lshlrev_b32_e32 v1, 2, v177
	v_add3_u32 v218, s0, v3, v1
	v_add_u32_e32 v1, 0, v10
	v_lshlrev_b32_e32 v2, 2, v166
	s_cmpk_lt_i32 s64, 0x1480
	v_add_u32_e32 v176, s0, v168
	s_mov_b32 s0, 0x20000
	v_add_u32_e32 v224, 0xd000, v1
	v_sub_u32_e32 v1, v167, v0
	s_cselect_b64 s[42:43], -1, 0
	v_lshl_add_u64 v[178:179], s[24:25], 0, v[4:5]
	v_lshl_add_u64 v[182:183], s[26:27], 0, v[4:5]
	v_lshl_add_u64 v[188:189], s[34:35], 0, v[4:5]
	v_lshl_add_u64 v[192:193], s[6:7], 0, v[4:5]
	v_lshl_add_u64 v[196:197], s[4:5], 0, v[4:5]
	v_cmp_gt_i32_e64 s[0:1], s0, v164
	s_lshl_b32 s68, s14, 9
	v_add3_u32 v222, 0, v9, v18
	v_add_u32_e32 v223, 0xfffffe00, v209
	v_or_b32_e32 v198, v19, v18
	v_mov_b32_e32 v199, v169
	v_add_u32_e32 v225, 0xffffff80, v1
	v_lshl_add_u32 v226, s2, 12, v200
	s_lshl_b32 s69, s14, 12
	s_mov_b64 s[52:53], 0
	s_add_i32 s70, 0, 0x12400
	v_lshlrev_b32_e32 v200, 1, v0
	s_movk_i32 s71, 0x27f
	s_mov_b32 s72, 0xc2fc0000
	s_mov_b32 s73, 0xff61b1e6
	s_mov_b32 s74, 0x40c00000
	s_mov_b32 s31, -1
	s_mov_b32 s45, -1
	v_lshlrev_b32_e32 v202, 1, v2
	v_mov_b32_e32 v227, 0x358637bd
	s_movk_i32 s75, 0x2c00
	s_mov_b64 s[46:47], 0x1000
	s_mov_b32 s76, 0x6800000
	s_mov_b32 s77, 0x1a900000
	s_mov_b32 s78, 0x6801000
	s_mov_b32 s79, 0x6802000
	s_mov_b32 s80, 0x6803000
	s_mov_b32 s81, 0x6804000
	s_mov_b64 s[48:49], 0x5000
	s_mov_b32 s82, 0x1ffff
	v_mov_b32_e32 v240, v169
	v_mov_b32_e32 v241, v169
	v_mov_b32_e32 v242, v169
	v_mov_b32_e32 v243, v169
	v_mov_b32_e32 v228, 0x42800000
	v_mov_b32_e32 v229, 0x7149f2ca
	s_branch .LBB0_309

.LBB0_324:
	v_add_u32_e32 v1, 0x200, v1
	v_cmp_lt_u32_e32 vcc, s71, v1
	ds_write_b128 v0, v[240:243]
	s_or_b64 s[56:57], vcc, s[56:57]
	v_add_u32_e32 v0, 0x2000, v0
	s_andn2_b64 exec, exec, s[56:57]
	s_cbranch_execnz .LBB0_324
	s_or_b64 exec, exec, s[56:57]
	s_add_i32 s38, s54, 1
	v_cvt_f32_u32_e32 v0, s38
	v_mov_b32_e32 v63, 0
	v_mov_b32_e32 v62, v63
	v_mov_b32_e32 v61, v63
	v_mul_f32_e32 v1, -2.0, v0
	v_cmp_gt_f32_e32 vcc, s72, v1
	s_and_b64 s[56:57], vcc, exec
	s_cselect_b32 s38, 0xffffffc0, 0
	v_cndmask_b32_e32 v1, 0, v228, vcc
	v_fmac_f32_e32 v1, -2.0, v0
	v_exp_f32_e32 v0, v1
	s_sub_i32 s58, s89, 63
	v_cvt_f32_i32_e32 v2, s58
	v_mov_b32_e32 v60, v63
	v_ldexp_f32 v0, v0, s38
	v_mul_f32_e32 v201, 0x3fb8aa3b, v0
	v_div_scale_f32 v0, s[56:57], v201, v201, v213
	v_rcp_f32_e32 v1, v0
	v_div_scale_f32 v3, vcc, v213, v201, v213
	v_mov_b32_e32 v59, v63
	v_fma_f32 v4, -v0, v1, 1.0
	v_fmac_f32_e32 v1, v4, v1
	v_mul_f32_e32 v4, v3, v1
	v_fma_f32 v5, -v0, v4, v3
	v_fmac_f32_e32 v4, v5, v1
	v_fma_f32 v0, -v0, v4, v3
	v_div_fmas_f32 v0, v0, v1, v4
	v_div_fixup_f32 v0, v0, v201, v213
	v_sub_f32_e32 v0, v2, v0
	v_mul_f32_e32 v0, 0x3c800000, v0
	v_ceil_f32_e32 v1, v0
	v_cvt_i32_f32_e32 v1, v1
	v_cmp_lt_f32_e32 vcc, 0, v0
	v_mov_b32_e32 v58, v63
	v_mov_b32_e32 v57, v63
	v_readfirstlane_b32 s38, v1
	s_min_i32 s38, s38, s86
	s_and_b64 s[56:57], vcc, exec
	s_cselect_b32 s38, s38, 0
	s_sub_i32 s86, s86, s38
	s_add_i32 s38, s86, 2
	s_cmp_gt_i32 s38, -1
	v_mov_b32_e32 v56, v63
	v_mov_b32_e32 v55, v63
	v_mov_b32_e32 v54, v63
	v_mov_b32_e32 v53, v63
	v_mov_b32_e32 v52, v63
	v_mov_b32_e32 v51, v63
	v_mov_b32_e32 v50, v63
	v_mov_b32_e32 v49, v63
	v_mov_b32_e32 v48, v63
	v_mov_b32_e32 v47, v63
	v_mov_b32_e32 v46, v63
	v_mov_b32_e32 v45, v63
	v_mov_b32_e32 v44, v63
	v_mov_b32_e32 v43, v63
	v_mov_b32_e32 v42, v63
	v_mov_b32_e32 v41, v63
	v_mov_b32_e32 v40, v63
	v_mov_b32_e32 v39, v63
	v_mov_b32_e32 v38, v63
	v_mov_b32_e32 v37, v63
	v_mov_b32_e32 v36, v63
	v_mov_b32_e32 v35, v63
	v_mov_b32_e32 v34, v63
	v_mov_b32_e32 v33, v63
	v_mov_b32_e32 v32, v63
	v_mov_b32_e32 v31, v63
	v_mov_b32_e32 v30, v63
	v_mov_b32_e32 v29, v63
	v_mov_b32_e32 v28, v63
	v_mov_b32_e32 v27, v63
	v_mov_b32_e32 v26, v63
	v_mov_b32_e32 v25, v63
	v_mov_b32_e32 v24, v63
	v_mov_b32_e32 v23, v63
	v_mov_b32_e32 v22, v63
	v_mov_b32_e32 v21, v63
	v_mov_b32_e32 v20, v63
	v_mov_b32_e32 v19, v63
	v_mov_b32_e32 v18, v63
	v_mov_b32_e32 v17, v63
	v_mov_b32_e32 v16, v63
	v_mov_b32_e32 v15, v63
	v_mov_b32_e32 v14, v63
	v_mov_b32_e32 v13, v63
	v_mov_b32_e32 v12, v63
	v_mov_b32_e32 v11, v63
	v_mov_b32_e32 v10, v63
	v_mov_b32_e32 v9, v63
	v_mov_b32_e32 v8, v63
	v_mov_b32_e32 v7, v63
	v_mov_b32_e32 v6, v63
	v_mov_b32_e32 v5, v63
	v_mov_b32_e32 v4, v63
	v_mov_b32_e32 v3, v63
	v_mov_b32_e32 v2, v63
	v_mov_b32_e32 v1, v63
	v_mov_b32_e32 v0, v63
	v_mov_b32_e32 v233, v63
	s_waitcnt vmcnt(0)
	s_waitcnt lgkmcnt(0)
	s_barrier
	s_cbranch_scc0 .LBB0_347
	s_cmp_lt_u32 s84, 2
	s_cselect_b64 s[56:57], -1, 0
	s_lshl_b32 s33, s33, 1
	v_cndmask_b32_e64 v203, 0, 1, s[56:57]
	s_sub_i32 s56, 0, s33
	s_and_b32 s55, s55, 3
	s_ashr_i32 s57, s56, 31
	s_add_i32 s86, s86, 3
	s_lshl_b32 s55, s55, 14
	s_lshl_b64 s[92:93], s[56:57], 7
	s_add_u32 s33, s92, s55
	s_mul_i32 s59, s65, 0x10080
	s_addc_u32 s55, s93, 0
	s_mul_hi_u32 s58, s65, 0x10080
	s_add_u32 s92, s33, s59
	s_addc_u32 s93, s55, s58
	s_mov_b32 s55, s39
	s_mul_hi_i32 s33, s56, 0x50000
	s_mul_i32 s56, s56, 0x50000
	s_lshl_b64 s[54:55], s[54:55], 8
	s_add_u32 s54, s54, s56
	s_addc_u32 s33, s55, s33
	s_add_u32 s54, s54, s88
	v_mov_b32_e32 v80, v169
	v_mov_b32_e32 v81, v169
	s_addc_u32 s55, s33, 0
	v_mov_b32_e32 v82, v169
	v_mov_b32_e32 v83, v169
	v_mov_b32_e32 v84, v169
	v_mov_b32_e32 v85, v169
	v_mov_b32_e32 v86, v169
	v_mov_b32_e32 v87, v169
	v_mov_b32_e32 v88, v169
	v_mov_b32_e32 v89, v169
	v_mov_b32_e32 v90, v169
	v_mov_b32_e32 v91, v169
	v_mov_b32_e32 v92, v169
	v_mov_b32_e32 v93, v169
	v_mov_b32_e32 v94, v169
	v_mov_b32_e32 v95, v169
	v_mov_b32_e32 v233, 0
	v_mov_b32_e32 v64, v253
	v_mov_b32_e32 v65, v253
	v_lshl_add_u32 v230, s85, 7, v214
	s_mov_b32 s90, 0
	v_lshl_add_u64 v[204:205], s[92:93], 0, v[198:199]
	v_lshl_add_u64 v[206:207], s[54:55], 0, v[170:171]
	v_add_u32_e32 v231, s87, v225
	v_mov_b32_e32 v144, 0
	v_mov_b32_e32 v145, 0
	v_mov_b32_e32 v146, 0
	v_mov_b32_e32 v147, 0
	v_mov_b32_e32 v148, 0
	v_mov_b32_e32 v149, 0
	v_mov_b32_e32 v150, 0
	v_mov_b32_e32 v151, 0
	v_mov_b32_e32 v66, v253
	v_mov_b32_e32 v67, v253
	v_mov_b32_e32 v68, v253
	v_mov_b32_e32 v69, v253
	v_mov_b32_e32 v70, v253
	v_mov_b32_e32 v71, v253
	v_mov_b32_e32 v72, v253
	v_mov_b32_e32 v73, v253
	v_mov_b32_e32 v74, v253
	v_mov_b32_e32 v75, v253
	v_mov_b32_e32 v76, v253
	v_mov_b32_e32 v77, v253
	v_mov_b32_e32 v78, v253
	v_mov_b32_e32 v79, v253
	v_mov_b32_e32 v232, 0
	v_mov_b32_e32 v0, 0
	v_mov_b32_e32 v1, v233
	v_mov_b32_e32 v2, v233
	v_mov_b32_e32 v3, v233
	v_mov_b32_e32 v4, v233
	v_mov_b32_e32 v5, v233
	v_mov_b32_e32 v6, v233
	v_mov_b32_e32 v7, v233
	v_mov_b32_e32 v8, v233
	v_mov_b32_e32 v9, v233
	v_mov_b32_e32 v10, v233
	v_mov_b32_e32 v11, v233
	v_mov_b32_e32 v12, v233
	v_mov_b32_e32 v13, v233
	v_mov_b32_e32 v14, v233
	v_mov_b32_e32 v15, v233
	v_mov_b32_e32 v16, 0
	v_mov_b32_e32 v17, v233
	v_mov_b32_e32 v18, v233
	v_mov_b32_e32 v19, v233
	v_mov_b32_e32 v20, v233
	v_mov_b32_e32 v21, v233
	v_mov_b32_e32 v22, v233
	v_mov_b32_e32 v23, v233
	v_mov_b32_e32 v24, v233
	v_mov_b32_e32 v25, v233
	v_mov_b32_e32 v26, v233
	v_mov_b32_e32 v27, v233
	v_mov_b32_e32 v28, v233
	v_mov_b32_e32 v29, v233
	v_mov_b32_e32 v30, v233
	v_mov_b32_e32 v31, v233
	v_mov_b32_e32 v32, 0
	v_mov_b32_e32 v33, v233
	v_mov_b32_e32 v34, v233
	v_mov_b32_e32 v35, v233
	v_mov_b32_e32 v36, v233
	v_mov_b32_e32 v37, v233
	v_mov_b32_e32 v38, v233
	v_mov_b32_e32 v39, v233
	v_mov_b32_e32 v40, v233
	v_mov_b32_e32 v41, v233
	v_mov_b32_e32 v42, v233
	v_mov_b32_e32 v43, v233
	v_mov_b32_e32 v44, v233
	v_mov_b32_e32 v45, v233
	v_mov_b32_e32 v46, v233
	v_mov_b32_e32 v47, v233
	v_mov_b32_e32 v48, 0
	v_mov_b32_e32 v49, v233
	v_mov_b32_e32 v50, v233
	v_mov_b32_e32 v51, v233
	v_mov_b32_e32 v52, v233
	v_mov_b32_e32 v53, v233
	v_mov_b32_e32 v54, v233
	v_mov_b32_e32 v55, v233
	v_mov_b32_e32 v56, v233
	v_mov_b32_e32 v57, v233
	v_mov_b32_e32 v58, v233
	v_mov_b32_e32 v59, v233
	v_mov_b32_e32 v60, v233
	v_mov_b32_e32 v61, v233
	v_mov_b32_e32 v62, v233
	v_mov_b32_e32 v63, v233

.LBB0_331:
	v_cvt_f32_i32_e32 v237, v231
	s_and_b32 s89, s87, 1
	s_mul_i32 s33, s89, 0x4800
	v_add_u32_e32 v234, s33, v215
	v_cmp_gt_u32_e32 vcc, s90, v203
	s_nop 1
	v_cndmask_b32_e32 v208, v229, v237, vcc
	v_add_f32_e32 v96, 0xc2000000, v208
	v_xor_b32_e32 v236, 0x80000000, v201
	v_fma_f32 v80, v236, |v96|, v80
	v_add_f32_e32 v96, 0xc2040000, v208
	v_fma_f32 v81, v236, |v96|, v81
	s_waitcnt lgkmcnt(1)
	v_mfma_f32_32x32x16_bf16 v[96:111], v[156:159], v[112:115], v[64:79]
	ds_read_b128 v[160:163], v235 offset:64
	v_add_f32_e32 v157, 0xc2080000, v208
	v_fma_f32 v82, v236, |v157|, v82
	v_add_f32_e32 v157, 0xc20c0000, v208
	v_fma_f32 v83, v236, |v157|, v83
	s_waitcnt lgkmcnt(1)
	v_mfma_f32_32x32x16_bf16 v[96:111], v[152:155], v[116:119], v[96:111]
	ds_read_b128 v[156:159], v235 offset:96
	v_add_f32_e32 v239, 0xc2100000, v208
	v_add_f32_e32 v152, 0xc2180000, v208
	v_fma_f32 v84, v236, |v239|, v84
	v_add_f32_e32 v239, 0xc2140000, v208
	v_fma_f32 v85, v236, |v239|, v85
	v_fma_f32 v86, v236, |v152|, v86
	v_add_f32_e32 v152, 0xc21c0000, v208
	v_fma_f32 v87, v236, |v152|, v87
	s_waitcnt lgkmcnt(1)
	v_mfma_f32_32x32x16_bf16 v[96:111], v[160:163], v[120:123], v[96:111]
	ds_read_b128 v[244:247], v234 offset:34816
	v_add_f32_e32 v153, 0xc2400000, v208
	v_fma_f32 v88, v236, |v153|, v88
	v_add_f32_e32 v153, 0xc2440000, v208
	v_fma_f32 v89, v236, |v153|, v89
	v_add_f32_e32 v153, 0xc2480000, v208
	v_fma_f32 v90, v236, |v153|, v90
	v_add_f32_e32 v153, 0xc24c0000, v208
	v_fma_f32 v91, v236, |v153|, v91
	s_waitcnt lgkmcnt(1)
	v_mfma_f32_32x32x16_bf16 v[96:111], v[156:159], v[124:127], v[96:111]
	ds_read_b128 v[152:155], v234 offset:34848
	v_add_f32_e32 v161, 0xc2500000, v208
	v_fma_f32 v92, v236, |v161|, v92
	v_add_f32_e32 v161, 0xc2540000, v208
	v_fma_f32 v93, v236, |v161|, v93
	v_add_f32_e32 v156, 0xc2580000, v208
	v_fma_f32 v94, v236, |v156|, v94
	v_add_f32_e32 v156, 0xc25c0000, v208
	v_fma_f32 v95, v236, |v156|, v95
	s_waitcnt lgkmcnt(1)
	v_mfma_f32_32x32x16_bf16 v[48:63], v[244:247], v[144:147], v[48:63]
	ds_read_b128 v[156:159], v234 offset:39424
.LBB0_333:
.LBB0_334:
	v_exp_f32_e32 v80, v80
	s_waitcnt lgkmcnt(1)
	v_mfma_f32_32x32x16_bf16 v[48:63], v[152:155], v[148:151], v[48:63]
	v_exp_f32_e32 v81, v81
	v_exp_f32_e32 v82, v82
	ds_read_b128 v[160:163], v234 offset:39456
	v_exp_f32_e32 v83, v83
	v_add_f32_e32 v238, 0, v80
	v_add_f32_e32 v152, v81, v238
	v_add_f32_e32 v152, v82, v152
	v_add_f32_e32 v238, v83, v152
	v_exp_f32_e32 v84, v84
	s_waitcnt lgkmcnt(1)
	v_mfma_f32_32x32x16_bf16 v[32:47], v[156:159], v[144:147], v[32:47]
	v_exp_f32_e32 v85, v85
	v_exp_f32_e32 v86, v86
	ds_read_b128 v[152:155], v234 offset:44032
	v_exp_f32_e32 v87, v87
	v_add_f32_e32 v238, v238, v84
	v_add_f32_e32 v156, v85, v238
	v_add_f32_e32 v156, v86, v156
	v_add_f32_e32 v238, v87, v156
	v_exp_f32_e32 v88, v88
	s_waitcnt lgkmcnt(1)
	v_mfma_f32_32x32x16_bf16 v[32:47], v[160:163], v[148:151], v[32:47]
	v_exp_f32_e32 v89, v89
	v_exp_f32_e32 v90, v90
	ds_read_b128 v[156:159], v234 offset:44064
	v_exp_f32_e32 v91, v91
	v_add_f32_e32 v238, v238, v88
	v_add_f32_e32 v160, v89, v238
	v_add_f32_e32 v160, v90, v160
	v_add_f32_e32 v160, v91, v160
	v_exp_f32_e32 v92, v92
	s_waitcnt lgkmcnt(1)
	v_mfma_f32_32x32x16_bf16 v[16:31], v[152:155], v[144:147], v[16:31]
	v_exp_f32_e32 v93, v93
	v_exp_f32_e32 v94, v94
	v_exp_f32_e32 v95, v95
	ds_read_b128 v[244:247], v234 offset:48640
	v_add_f32_e32 v160, v160, v92
	v_add_f32_e32 v152, v93, v160
	v_add_f32_e32 v152, v94, v152
	v_add_f32_e32 v238, v95, v152
	s_waitcnt lgkmcnt(1)
	v_mfma_f32_32x32x16_bf16 v[16:31], v[156:159], v[148:151], v[16:31]
	ds_read_b128 v[248:251], v234 offset:48672
	v_cvt_pk_bf16_f32 v152, v80, v81
	v_cvt_pk_bf16_f32 v153, v82, v83
	v_cvt_pk_bf16_f32 v154, v84, v85
	v_cvt_pk_bf16_f32 v155, v86, v87
	s_waitcnt lgkmcnt(1)
	v_mfma_f32_32x32x16_bf16 v[0:15], v[244:247], v[144:147], v[0:15]
	ds_read_b128 v[160:163], v235 offset:8704
	v_cvt_pk_bf16_f32 v156, v88, v89
	v_cvt_pk_bf16_f32 v157, v90, v91
	v_cvt_pk_bf16_f32 v158, v92, v93
	v_cvt_pk_bf16_f32 v159, v94, v95
	s_waitcnt lgkmcnt(1)
	v_mfma_f32_32x32x16_bf16 v[0:15], v[248:251], v[148:151], v[0:15]
	ds_read_b128 v[144:147], v235 offset:8736
	v_add_f32_e32 v238, v238, v233
.LBB0_336:
	v_cmp_ge_u32_e32 vcc, s90, v203
	v_add_f32_e32 v80, 0x42800000, v237
	s_and_b64 vcc, vcc, s[56:57]
	v_cndmask_b32_e32 v208, v229, v80, vcc
	v_add_f32_e32 v80, -1.0, v208
	v_fma_f32 v97, v236, |v80|, v97
	s_waitcnt lgkmcnt(1)
	v_mfma_f32_32x32x16_bf16 v[80:95], v[160:163], v[112:115], v[64:79]
	ds_read_b128 v[148:151], v235 offset:8768
	v_fma_f32 v96, v236, |v208|, v96
	v_add_f32_e32 v237, -2.0, v208
	v_fma_f32 v98, v236, |v237|, v98
	v_add_f32_e32 v160, 0xc0400000, v208
	v_fma_f32 v99, v236, |v160|, v99
	s_waitcnt lgkmcnt(1)
	v_mfma_f32_32x32x16_bf16 v[80:95], v[144:147], v[116:119], v[80:95]
	ds_read_b128 v[160:163], v235 offset:8800
	v_add_f32_e32 v235, -4.0, v208
	v_add_f32_e32 v144, 0xc0c00000, v208
	v_fma_f32 v100, v236, |v235|, v100
	v_add_f32_e32 v235, 0xc0a00000, v208
	v_fma_f32 v101, v236, |v235|, v101
	v_fma_f32 v102, v236, |v144|, v102
	v_add_f32_e32 v144, 0xc0e00000, v208
	v_fma_f32 v103, v236, |v144|, v103
	s_waitcnt lgkmcnt(1)
	v_mfma_f32_32x32x16_bf16 v[80:95], v[148:151], v[120:123], v[80:95]
	ds_read_b128 v[244:247], v234 offset:34880
	v_add_f32_e32 v145, 0xc1800000, v208
	v_fma_f32 v104, v236, |v145|, v104
	v_add_f32_e32 v145, 0xc1880000, v208
	v_fma_f32 v105, v236, |v145|, v105
	v_add_f32_e32 v145, 0xc1900000, v208
	v_fma_f32 v106, v236, |v145|, v106
	v_add_f32_e32 v145, 0xc1980000, v208
	v_fma_f32 v107, v236, |v145|, v107
	s_waitcnt lgkmcnt(1)
	v_mfma_f32_32x32x16_bf16 v[80:95], v[160:163], v[124:127], v[80:95]
	ds_read_b128 v[144:147], v234 offset:34912
	v_add_f32_e32 v149, 0xc1a00000, v208
	v_fma_f32 v108, v236, |v149|, v108
	v_add_f32_e32 v149, 0xc1a80000, v208
	v_fma_f32 v109, v236, |v149|, v109
	v_add_f32_e32 v149, 0xc1b00000, v208
	v_fma_f32 v110, v236, |v149|, v110
	v_add_f32_e32 v149, 0xc1b80000, v208
	v_fma_f32 v111, v236, |v149|, v111
	s_waitcnt lgkmcnt(1)
	v_mfma_f32_32x32x16_bf16 v[48:63], v[244:247], v[152:155], v[48:63]
	ds_read_b128 v[148:151], v234 offset:39488
.LBB0_338:
.LBB0_339:
	v_exp_f32_e32 v96, v96
	s_waitcnt lgkmcnt(1)
	v_mfma_f32_32x32x16_bf16 v[48:63], v[144:147], v[156:159], v[48:63]
	v_exp_f32_e32 v97, v97
	v_exp_f32_e32 v98, v98
	v_exp_f32_e32 v99, v99
	ds_read_b128 v[244:247], v234 offset:39520
	v_add_f32_e32 v161, 0, v96
	v_add_f32_e32 v144, v97, v161
	v_add_f32_e32 v144, v98, v144
	v_add_f32_e32 v161, v99, v144
	v_exp_f32_e32 v100, v100
	s_waitcnt lgkmcnt(1)
	v_mfma_f32_32x32x16_bf16 v[32:47], v[148:151], v[152:155], v[32:47]
	v_exp_f32_e32 v101, v101
	v_exp_f32_e32 v102, v102
	ds_read_b128 v[144:147], v234 offset:44096
	v_exp_f32_e32 v103, v103
	v_add_f32_e32 v161, v161, v100
	v_add_f32_e32 v148, v101, v161
	v_add_f32_e32 v148, v102, v148
	v_add_f32_e32 v161, v103, v148
	v_exp_f32_e32 v104, v104
	s_waitcnt lgkmcnt(1)
	v_mfma_f32_32x32x16_bf16 v[32:47], v[244:247], v[156:159], v[32:47]
	v_exp_f32_e32 v105, v105
	v_exp_f32_e32 v106, v106
	ds_read_b128 v[148:151], v234 offset:44128
	v_exp_f32_e32 v107, v107
	v_add_f32_e32 v161, v161, v104
	v_add_f32_e32 v161, v105, v161
	v_add_f32_e32 v161, v106, v161
	v_add_f32_e32 v161, v107, v161
	v_exp_f32_e32 v108, v108
	s_waitcnt lgkmcnt(1)
	v_mfma_f32_32x32x16_bf16 v[16:31], v[144:147], v[152:155], v[16:31]
	v_exp_f32_e32 v109, v109
	v_exp_f32_e32 v110, v110
	v_exp_f32_e32 v111, v111
	ds_read_b128 v[244:247], v234 offset:48704
	v_add_f32_e32 v161, v161, v108
	v_add_f32_e32 v144, v109, v161
	v_add_f32_e32 v144, v110, v144
	v_add_f32_e32 v233, v111, v144
	s_waitcnt lgkmcnt(1)
	v_mfma_f32_32x32x16_bf16 v[16:31], v[148:151], v[156:159], v[16:31]
	ds_read_b128 v[234:237], v234 offset:48736
	v_cvt_pk_bf16_f32 v144, v96, v97
	v_cvt_pk_bf16_f32 v145, v98, v99
	v_cvt_pk_bf16_f32 v146, v100, v101
	v_cvt_pk_bf16_f32 v147, v102, v103
	s_waitcnt lgkmcnt(1)
	v_mfma_f32_32x32x16_bf16 v[0:15], v[244:247], v[152:155], v[0:15]
	v_cvt_pk_bf16_f32 v148, v104, v105
	v_cvt_pk_bf16_f32 v149, v106, v107
	v_cvt_pk_bf16_f32 v150, v108, v109
	v_cvt_pk_bf16_f32 v151, v110, v111
	s_waitcnt lgkmcnt(0)
	v_mfma_f32_32x32x16_bf16 v[0:15], v[234:237], v[156:159], v[0:15]
	v_add_f32_e32 v233, v233, v238

	.amdhsa_kernel _Z14fwd_megakernel4Args
		.amdhsa_group_segment_fixed_size 0
		.amdhsa_private_segment_fixed_size 0
		.amdhsa_kernarg_size 432
		.amdhsa_user_sgpr_count 2
		.amdhsa_user_sgpr_dispatch_ptr 0
		.amdhsa_user_sgpr_queue_ptr 0
		.amdhsa_user_sgpr_kernarg_segment_ptr 1
		.amdhsa_user_sgpr_dispatch_id 0
		.amdhsa_user_sgpr_kernarg_preload_length 0
		.amdhsa_user_sgpr_kernarg_preload_offset 0
		.amdhsa_user_sgpr_private_segment_size 0
		.amdhsa_uses_dynamic_stack 0
		.amdhsa_enable_private_segment 0
		.amdhsa_system_sgpr_workgroup_id_x 1
		.amdhsa_system_sgpr_workgroup_id_y 0
		.amdhsa_system_sgpr_workgroup_id_z 0
		.amdhsa_system_sgpr_workgroup_info 0
		.amdhsa_system_vgpr_workitem_id 2
		.amdhsa_next_free_vgpr 256
		.amdhsa_next_free_sgpr 98
		.amdhsa_accum_offset 256
		.amdhsa_reserve_vcc 1
		.amdhsa_float_round_mode_32 0
		.amdhsa_float_round_mode_16_64 0
		.amdhsa_float_denorm_mode_32 3
		.amdhsa_float_denorm_mode_16_64 3
		.amdhsa_dx10_clamp 1
		.amdhsa_ieee_mode 1
		.amdhsa_fp16_overflow 0
		.amdhsa_tg_split 0
		.amdhsa_exception_fp_ieee_invalid_op 0
		.amdhsa_exception_fp_denorm_src 0
		.amdhsa_exception_fp_ieee_div_zero 0
		.amdhsa_exception_fp_ieee_overflow 0
		.amdhsa_exception_fp_ieee_underflow 0
		.amdhsa_exception_fp_ieee_inexact 0
		.amdhsa_exception_int_div_zero 0
	.end_amdhsa_kernel

amdhsa.kernels:
  - .agpr_count:     0
    .args:
      - .offset:         0
        .size:           176
        .value_kind:     by_value
      - .offset:         176
        .size:           4
        .value_kind:     hidden_block_count_x
      - .offset:         180
        .size:           4
        .value_kind:     hidden_block_count_y
      - .offset:         184
        .size:           4
        .value_kind:     hidden_block_count_z
      - .offset:         188
        .size:           2
        .value_kind:     hidden_group_size_x
      - .offset:         190
        .size:           2
        .value_kind:     hidden_group_size_y
      - .offset:         192
        .size:           2
        .value_kind:     hidden_group_size_z
      - .offset:         194
        .size:           2
        .value_kind:     hidden_remainder_x
      - .offset:         196
        .size:           2
        .value_kind:     hidden_remainder_y
      - .offset:         198
        .size:           2
        .value_kind:     hidden_remainder_z
      - .offset:         216
        .size:           8
        .value_kind:     hidden_global_offset_x
      - .offset:         224
        .size:           8
        .value_kind:     hidden_global_offset_y
      - .offset:         232
        .size:           8
        .value_kind:     hidden_global_offset_z
      - .offset:         240
        .size:           2
        .value_kind:     hidden_grid_dims
      - .offset:         264
        .size:           8
        .value_kind:     hidden_multigrid_sync_arg
      - .offset:         296
        .size:           4
        .value_kind:     hidden_dynamic_lds_size
    .group_segment_fixed_size: 0
    .kernarg_segment_align: 8
    .kernarg_segment_size: 432
    .language:       OpenCL C
    .language_version:
      - 2
      - 0
    .max_flat_workgroup_size: 512
    .name:           _Z14fwd_megakernel4Args
    .private_segment_fixed_size: 0
    .sgpr_count:     104
    .sgpr_spill_count: 12
    .symbol:         _Z14fwd_megakernel4Args.kd
    .uniform_work_group_size: 1
    .uses_dynamic_stack: false
    .vgpr_count:     256
    .vgpr_spill_count: 0
    .wavefront_size: 64
